# B3 prompt-row loop hand-written and software-pipelined (next group's loads in flight)
# speedup vs baseline: 1.1557x; 1.0011x over previous
.LBB0_142:
	v_lshrrev_b32_e32 v170, 6, v133
	v_and_b32_e32 v171, 63, v133
	v_lshlrev_b32_e32 v172, 4, v170
	v_add_u32_e32 v172, 0x19110000, v172
	v_lshlrev_b32_e32 v173, 6, v170
	v_add_u32_e32 v173, v173, v171
	v_lshlrev_b32_e32 v174, 2, v173
	v_add_u32_e32 v174, 0x19314000, v174
	v_lshlrev_b32_e32 v175, 1, v173
	v_add_u32_e32 v176, 0x4580200, v175
	v_add_u32_e32 v175, 0x6a01100, v175
	v_mul_u32_u24_e32 v177, 0x300000, v170
	v_lshl_add_u32 v177, v171, 2, v177
	v_add_u32_e32 v177, 0xcf90500, v177
	v_readlane_b32 s21, v212, 7
	s_add_i32 s0, s24, 0
	s_lshl_b32 s1, s0, 7
	v_add_u32_e32 v107, s1, v172
	global_load_dwordx4 v[100:103], v107, s[94:95]
	s_lshr_b32 s1, s0, 11
	s_mul_i32 s1, s1, 0x1800000
	s_and_b32 s2, s0, 0x7ff
	s_mul_i32 s2, s2, 0x600
	s_add_i32 s1, s1, s2
	v_add_u32_e32 v107, s1, v177
	global_load_dword v104, v107, s[94:95]
	s_lshl_b32 s1, s0, 11
	v_add_u32_e32 v107, s1, v174
	global_load_dword v105, v107, s[94:95]
	s_mul_i32 s1, s0, 0x1900
	v_add_u32_e32 v107, s1, v175
	global_load_ushort v106, v107, s[94:95]
	s_add_i32 s0, s24, 1
	s_lshl_b32 s1, s0, 7
	v_add_u32_e32 v115, s1, v172
	global_load_dwordx4 v[108:111], v115, s[94:95]
	s_lshr_b32 s1, s0, 11
	s_mul_i32 s1, s1, 0x1800000
	s_and_b32 s2, s0, 0x7ff
	s_mul_i32 s2, s2, 0x600
	s_add_i32 s1, s1, s2
	v_add_u32_e32 v115, s1, v177
	global_load_dword v112, v115, s[94:95]
	s_lshl_b32 s1, s0, 11
	v_add_u32_e32 v115, s1, v174
	global_load_dword v113, v115, s[94:95]
	s_mul_i32 s1, s0, 0x1900
	v_add_u32_e32 v115, s1, v175
	global_load_ushort v114, v115, s[94:95]
	s_add_i32 s0, s24, 2
	s_lshl_b32 s1, s0, 7
	v_add_u32_e32 v123, s1, v172
	global_load_dwordx4 v[116:119], v123, s[94:95]
	s_lshr_b32 s1, s0, 11
	s_mul_i32 s1, s1, 0x1800000
	s_and_b32 s2, s0, 0x7ff
	s_mul_i32 s2, s2, 0x600
	s_add_i32 s1, s1, s2
	v_add_u32_e32 v123, s1, v177
	global_load_dword v120, v123, s[94:95]
	s_lshl_b32 s1, s0, 11
	v_add_u32_e32 v123, s1, v174
	global_load_dword v121, v123, s[94:95]
	s_mul_i32 s1, s0, 0x1900
	v_add_u32_e32 v123, s1, v175
	global_load_ushort v122, v123, s[94:95]
	s_add_i32 s0, s24, 3
	s_lshl_b32 s1, s0, 7
	v_add_u32_e32 v131, s1, v172
	global_load_dwordx4 v[124:127], v131, s[94:95]
	s_lshr_b32 s1, s0, 11
	s_mul_i32 s1, s1, 0x1800000
	s_and_b32 s2, s0, 0x7ff
	s_mul_i32 s2, s2, 0x600
	s_add_i32 s1, s1, s2
	v_add_u32_e32 v131, s1, v177
	global_load_dword v128, v131, s[94:95]
	s_lshl_b32 s1, s0, 11
	v_add_u32_e32 v131, s1, v174
	global_load_dword v129, v131, s[94:95]
	s_mul_i32 s1, s0, 0x1900
	v_add_u32_e32 v131, s1, v175
	global_load_ushort v130, v131, s[94:95]
.Lb3_loop:
	s_add_i32 vcc_lo, s24, s21
	s_cmpk_gt_i32 vcc_lo, 0x3fff
	s_cbranch_scc1 .Lb3_last0
	s_add_i32 s0, vcc_lo, 0
	s_lshl_b32 s1, s0, 7
	v_add_u32_e32 v141, s1, v172
	global_load_dwordx4 v[134:137], v141, s[94:95]
	s_lshr_b32 s1, s0, 11
	s_mul_i32 s1, s1, 0x1800000
	s_and_b32 s2, s0, 0x7ff
	s_mul_i32 s2, s2, 0x600
	s_add_i32 s1, s1, s2
	v_add_u32_e32 v141, s1, v177
	global_load_dword v138, v141, s[94:95]
	s_lshl_b32 s1, s0, 11
	v_add_u32_e32 v141, s1, v174
	global_load_dword v139, v141, s[94:95]
	s_mul_i32 s1, s0, 0x1900
	v_add_u32_e32 v141, s1, v175
	global_load_ushort v140, v141, s[94:95]
	s_add_i32 s0, vcc_lo, 1
	s_lshl_b32 s1, s0, 7
	v_add_u32_e32 v149, s1, v172
	global_load_dwordx4 v[142:145], v149, s[94:95]
	s_lshr_b32 s1, s0, 11
	s_mul_i32 s1, s1, 0x1800000
	s_and_b32 s2, s0, 0x7ff
	s_mul_i32 s2, s2, 0x600
	s_add_i32 s1, s1, s2
	v_add_u32_e32 v149, s1, v177
	global_load_dword v146, v149, s[94:95]
	s_lshl_b32 s1, s0, 11
	v_add_u32_e32 v149, s1, v174
	global_load_dword v147, v149, s[94:95]
	s_mul_i32 s1, s0, 0x1900
	v_add_u32_e32 v149, s1, v175
	global_load_ushort v148, v149, s[94:95]
	s_add_i32 s0, vcc_lo, 2
	s_lshl_b32 s1, s0, 7
	v_add_u32_e32 v157, s1, v172
	global_load_dwordx4 v[150:153], v157, s[94:95]
	s_lshr_b32 s1, s0, 11
	s_mul_i32 s1, s1, 0x1800000
	s_and_b32 s2, s0, 0x7ff
	s_mul_i32 s2, s2, 0x600
	s_add_i32 s1, s1, s2
	v_add_u32_e32 v157, s1, v177
	global_load_dword v154, v157, s[94:95]
	s_lshl_b32 s1, s0, 11
	v_add_u32_e32 v157, s1, v174
	global_load_dword v155, v157, s[94:95]
	s_mul_i32 s1, s0, 0x1900
	v_add_u32_e32 v157, s1, v175
	global_load_ushort v156, v157, s[94:95]
	s_add_i32 s0, vcc_lo, 3
	s_lshl_b32 s1, s0, 7
	v_add_u32_e32 v165, s1, v172
	global_load_dwordx4 v[158:161], v165, s[94:95]
	s_lshr_b32 s1, s0, 11
	s_mul_i32 s1, s1, 0x1800000
	s_and_b32 s2, s0, 0x7ff
	s_mul_i32 s2, s2, 0x600
	s_add_i32 s1, s1, s2
	v_add_u32_e32 v165, s1, v177
	global_load_dword v162, v165, s[94:95]
	s_lshl_b32 s1, s0, 11
	v_add_u32_e32 v165, s1, v174
	global_load_dword v163, v165, s[94:95]
	s_mul_i32 s1, s0, 0x1900
	v_add_u32_e32 v165, s1, v175
	global_load_ushort v164, v165, s[94:95]
	s_waitcnt vmcnt(16)
	v_fmac_f32_e32 v105, v102, v104
	v_fmac_f32_e32 v113, v110, v112
	v_fmac_f32_e32 v121, v118, v120
	v_fmac_f32_e32 v129, v126, v128
	v_add_f32_dpp v178, v105, v105 quad_perm:[1,0,3,2] row_mask:0xf bank_mask:0xf bound_ctrl:1
	v_add_f32_dpp v179, v113, v113 quad_perm:[1,0,3,2] row_mask:0xf bank_mask:0xf bound_ctrl:1
	v_add_f32_dpp v180, v121, v121 quad_perm:[1,0,3,2] row_mask:0xf bank_mask:0xf bound_ctrl:1
	v_add_f32_dpp v181, v129, v129 quad_perm:[1,0,3,2] row_mask:0xf bank_mask:0xf bound_ctrl:1
	v_add_f32_dpp v178, v178, v178 quad_perm:[2,3,0,1] row_mask:0xf bank_mask:0xf bound_ctrl:1
	v_add_f32_dpp v179, v179, v179 quad_perm:[2,3,0,1] row_mask:0xf bank_mask:0xf bound_ctrl:1
	v_add_f32_dpp v180, v180, v180 quad_perm:[2,3,0,1] row_mask:0xf bank_mask:0xf bound_ctrl:1
	v_add_f32_dpp v181, v181, v181 quad_perm:[2,3,0,1] row_mask:0xf bank_mask:0xf bound_ctrl:1
	v_add_f32_dpp v178, v178, v178 row_half_mirror row_mask:0xf bank_mask:0xf bound_ctrl:1
	v_add_f32_dpp v179, v179, v179 row_half_mirror row_mask:0xf bank_mask:0xf bound_ctrl:1
	v_add_f32_dpp v180, v180, v180 row_half_mirror row_mask:0xf bank_mask:0xf bound_ctrl:1
	v_add_f32_dpp v181, v181, v181 row_half_mirror row_mask:0xf bank_mask:0xf bound_ctrl:1
	v_add_f32_dpp v178, v178, v178 row_mirror row_mask:0xf bank_mask:0xf bound_ctrl:1
	v_add_f32_dpp v179, v179, v179 row_mirror row_mask:0xf bank_mask:0xf bound_ctrl:1
	v_add_f32_dpp v180, v180, v180 row_mirror row_mask:0xf bank_mask:0xf bound_ctrl:1
	v_add_f32_dpp v181, v181, v181 row_mirror row_mask:0xf bank_mask:0xf bound_ctrl:1
	v_mov_b32_e32 v182, v65
	v_mov_b32_e32 v183, v65
	v_mov_b32_e32 v184, v65
	v_mov_b32_e32 v185, v65
	v_mov_b32_dpp v182, v178 row_bcast:15 row_mask:0xa bank_mask:0xf
	v_mov_b32_dpp v183, v179 row_bcast:15 row_mask:0xa bank_mask:0xf
	v_mov_b32_dpp v184, v180 row_bcast:15 row_mask:0xa bank_mask:0xf
	v_mov_b32_dpp v185, v181 row_bcast:15 row_mask:0xa bank_mask:0xf
	v_add_f32_e32 v178, v178, v182
	v_add_f32_e32 v179, v179, v183
	v_add_f32_e32 v180, v180, v184
	v_add_f32_e32 v181, v181, v185
	v_mov_b32_e32 v182, v65
	v_mov_b32_e32 v183, v65
	v_mov_b32_e32 v184, v65
	v_mov_b32_e32 v185, v65
	v_mov_b32_dpp v182, v178 row_bcast:31 row_mask:0xc bank_mask:0xf
	v_mov_b32_dpp v183, v179 row_bcast:31 row_mask:0xc bank_mask:0xf
	v_mov_b32_dpp v184, v180 row_bcast:31 row_mask:0xc bank_mask:0xf
	v_mov_b32_dpp v185, v181 row_bcast:31 row_mask:0xc bank_mask:0xf
	v_add_f32_e32 v178, v178, v182
	v_add_f32_e32 v179, v179, v183
	v_add_f32_e32 v180, v180, v184
	v_add_f32_e32 v181, v181, v185
	v_readlane_b32 s0, v178, 63
	v_readlane_b32 s1, v179, 63
	v_readlane_b32 s2, v180, 63
	v_readlane_b32 s20, v181, 63
	v_lshlrev_b32_e32 v106, 16, v106
	v_lshlrev_b32_e32 v114, 16, v114
	v_lshlrev_b32_e32 v122, 16, v122
	v_lshlrev_b32_e32 v130, 16, v130
	v_fmac_f32_e32 v105, s0, v193
	v_fmac_f32_e32 v113, s1, v193
	v_fmac_f32_e32 v121, s2, v193
	v_fmac_f32_e32 v129, s20, v193
	v_mul_f32_e32 v178, v105, v105
	v_mul_f32_e32 v179, v113, v113
	v_mul_f32_e32 v180, v121, v121
	v_mul_f32_e32 v181, v129, v129
	v_mov_b32_e32 v182, v65
	v_mov_b32_e32 v183, v65
	v_mov_b32_e32 v184, v65
	v_mov_b32_e32 v185, v65
	v_mov_b32_dpp v182, v178 quad_perm:[1,0,3,2] row_mask:0xf bank_mask:0xf
	v_mov_b32_dpp v183, v179 quad_perm:[1,0,3,2] row_mask:0xf bank_mask:0xf
	v_mov_b32_dpp v184, v180 quad_perm:[1,0,3,2] row_mask:0xf bank_mask:0xf
	v_mov_b32_dpp v185, v181 quad_perm:[1,0,3,2] row_mask:0xf bank_mask:0xf
	v_fmac_f32_e32 v182, v105, v105
	v_fmac_f32_e32 v183, v113, v113
	v_fmac_f32_e32 v184, v121, v121
	v_fmac_f32_e32 v185, v129, v129
	v_mov_b32_e32 v178, v182
	v_mov_b32_e32 v179, v183
	v_mov_b32_e32 v180, v184
	v_mov_b32_e32 v181, v185
	v_add_f32_dpp v178, v178, v178 quad_perm:[2,3,0,1] row_mask:0xf bank_mask:0xf bound_ctrl:1
	v_add_f32_dpp v179, v179, v179 quad_perm:[2,3,0,1] row_mask:0xf bank_mask:0xf bound_ctrl:1
	v_add_f32_dpp v180, v180, v180 quad_perm:[2,3,0,1] row_mask:0xf bank_mask:0xf bound_ctrl:1
	v_add_f32_dpp v181, v181, v181 quad_perm:[2,3,0,1] row_mask:0xf bank_mask:0xf bound_ctrl:1
	v_add_f32_dpp v178, v178, v178 row_half_mirror row_mask:0xf bank_mask:0xf bound_ctrl:1
	v_add_f32_dpp v179, v179, v179 row_half_mirror row_mask:0xf bank_mask:0xf bound_ctrl:1
	v_add_f32_dpp v180, v180, v180 row_half_mirror row_mask:0xf bank_mask:0xf bound_ctrl:1
	v_add_f32_dpp v181, v181, v181 row_half_mirror row_mask:0xf bank_mask:0xf bound_ctrl:1
	v_add_f32_dpp v178, v178, v178 row_mirror row_mask:0xf bank_mask:0xf bound_ctrl:1
	v_add_f32_dpp v179, v179, v179 row_mirror row_mask:0xf bank_mask:0xf bound_ctrl:1
	v_add_f32_dpp v180, v180, v180 row_mirror row_mask:0xf bank_mask:0xf bound_ctrl:1
	v_add_f32_dpp v181, v181, v181 row_mirror row_mask:0xf bank_mask:0xf bound_ctrl:1
	v_mov_b32_e32 v182, v65
	v_mov_b32_e32 v183, v65
	v_mov_b32_e32 v184, v65
	v_mov_b32_e32 v185, v65
	v_mov_b32_dpp v182, v178 row_bcast:15 row_mask:0xa bank_mask:0xf
	v_mov_b32_dpp v183, v179 row_bcast:15 row_mask:0xa bank_mask:0xf
	v_mov_b32_dpp v184, v180 row_bcast:15 row_mask:0xa bank_mask:0xf
	v_mov_b32_dpp v185, v181 row_bcast:15 row_mask:0xa bank_mask:0xf
	v_add_f32_e32 v178, v178, v182
	v_add_f32_e32 v179, v179, v183
	v_add_f32_e32 v180, v180, v184
	v_add_f32_e32 v181, v181, v185
	v_mov_b32_e32 v182, v65
	v_mov_b32_e32 v183, v65
	v_mov_b32_e32 v184, v65
	v_mov_b32_e32 v185, v65
	v_mov_b32_dpp v182, v178 row_bcast:31 row_mask:0xc bank_mask:0xf
	v_mov_b32_dpp v183, v179 row_bcast:31 row_mask:0xc bank_mask:0xf
	v_mov_b32_dpp v184, v180 row_bcast:31 row_mask:0xc bank_mask:0xf
	v_mov_b32_dpp v185, v181 row_bcast:31 row_mask:0xc bank_mask:0xf
	v_add_f32_e32 v178, v178, v182
	v_add_f32_e32 v179, v179, v183
	v_add_f32_e32 v180, v180, v184
	v_add_f32_e32 v181, v181, v185
	v_readlane_b32 s0, v178, 63
	v_readlane_b32 s1, v179, 63
	v_readlane_b32 s2, v180, 63
	v_readlane_b32 s20, v181, 63
	v_mul_f32_e32 v182, 0xbfb8aa3b, v106
	v_mul_f32_e32 v183, 0xbfb8aa3b, v114
	v_mul_f32_e32 v184, 0xbfb8aa3b, v122
	v_mul_f32_e32 v185, 0xbfb8aa3b, v130
	v_fma_f32 v178, s0, v194, v189
	v_fma_f32 v179, s1, v194, v189
	v_fma_f32 v180, s2, v194, v189
	v_fma_f32 v181, s20, v194, v189
	v_exp_f32_e32 v182, v182
	v_exp_f32_e32 v183, v183
	v_exp_f32_e32 v184, v184
	v_exp_f32_e32 v185, v185
	v_rsq_f32_e32 v178, v178
	v_rsq_f32_e32 v179, v179
	v_rsq_f32_e32 v180, v180
	v_rsq_f32_e32 v181, v181
	v_add_f32_e32 v182, 1.0, v182
	v_add_f32_e32 v183, 1.0, v183
	v_add_f32_e32 v184, 1.0, v184
	v_add_f32_e32 v185, 1.0, v185
	v_mul_f32_e32 v178, v105, v178
	v_mul_f32_e32 v179, v113, v179
	v_mul_f32_e32 v180, v121, v180
	v_mul_f32_e32 v181, v129, v181
	v_rcp_f32_e32 v182, v182
	v_rcp_f32_e32 v183, v183
	v_rcp_f32_e32 v184, v184
	v_rcp_f32_e32 v185, v185
	v_fma_f32 v178, v42, v178, v43
	v_fma_f32 v179, v42, v179, v43
	v_fma_f32 v180, v42, v180, v43
	v_fma_f32 v181, v42, v181, v43
	v_fmac_f32_e32 v178, v100, v104
	v_fmac_f32_e32 v179, v108, v112
	v_fmac_f32_e32 v180, v116, v120
	v_fmac_f32_e32 v181, v124, v128
	v_mul_f32_e32 v182, v182, v106
	v_mul_f32_e32 v183, v183, v114
	v_mul_f32_e32 v184, v184, v122
	v_mul_f32_e32 v185, v185, v130
	v_mul_f32_e32 v178, v182, v178
	v_mul_f32_e32 v179, v183, v179
	v_mul_f32_e32 v180, v184, v180
	v_mul_f32_e32 v181, v185, v181
	v_bfe_u32 v182, v178, 16, 1
	v_bfe_u32 v183, v179, 16, 1
	v_bfe_u32 v184, v180, 16, 1
	v_bfe_u32 v185, v181, 16, 1
	v_add3_u32 v178, v178, v182, s27
	v_add3_u32 v179, v179, v183, s27
	v_add3_u32 v180, v180, v184, s27
	v_add3_u32 v181, v181, v185, s27
	s_add_i32 s0, s24, 0
	s_lshl_b32 s0, s0, 11
	v_add_u32_e32 v182, s0, v176
	s_add_i32 s0, s24, 1
	s_lshl_b32 s0, s0, 11
	v_add_u32_e32 v183, s0, v176
	s_add_i32 s0, s24, 2
	s_lshl_b32 s0, s0, 11
	v_add_u32_e32 v184, s0, v176
	s_add_i32 s0, s24, 3
	s_lshl_b32 s0, s0, 11
	v_add_u32_e32 v185, s0, v176
	global_store_short_d16_hi v182, v178, s[94:95]
	global_store_short_d16_hi v183, v179, s[94:95]
	global_store_short_d16_hi v184, v180, s[94:95]
	global_store_short_d16_hi v185, v181, s[94:95]
	s_mov_b32 s24, vcc_lo
	s_add_i32 vcc_lo, s24, s21
	s_cmpk_gt_i32 vcc_lo, 0x3fff
	s_cbranch_scc1 .Lb3_last1
	s_add_i32 s0, vcc_lo, 0
	s_lshl_b32 s1, s0, 7
	v_add_u32_e32 v107, s1, v172
	global_load_dwordx4 v[100:103], v107, s[94:95]
	s_lshr_b32 s1, s0, 11
	s_mul_i32 s1, s1, 0x1800000
	s_and_b32 s2, s0, 0x7ff
	s_mul_i32 s2, s2, 0x600
	s_add_i32 s1, s1, s2
	v_add_u32_e32 v107, s1, v177
	global_load_dword v104, v107, s[94:95]
	s_lshl_b32 s1, s0, 11
	v_add_u32_e32 v107, s1, v174
	global_load_dword v105, v107, s[94:95]
	s_mul_i32 s1, s0, 0x1900
	v_add_u32_e32 v107, s1, v175
	global_load_ushort v106, v107, s[94:95]
	s_add_i32 s0, vcc_lo, 1
	s_lshl_b32 s1, s0, 7
	v_add_u32_e32 v115, s1, v172
	global_load_dwordx4 v[108:111], v115, s[94:95]
	s_lshr_b32 s1, s0, 11
	s_mul_i32 s1, s1, 0x1800000
	s_and_b32 s2, s0, 0x7ff
	s_mul_i32 s2, s2, 0x600
	s_add_i32 s1, s1, s2
	v_add_u32_e32 v115, s1, v177
	global_load_dword v112, v115, s[94:95]
	s_lshl_b32 s1, s0, 11
	v_add_u32_e32 v115, s1, v174
	global_load_dword v113, v115, s[94:95]
	s_mul_i32 s1, s0, 0x1900
	v_add_u32_e32 v115, s1, v175
	global_load_ushort v114, v115, s[94:95]
	s_add_i32 s0, vcc_lo, 2
	s_lshl_b32 s1, s0, 7
	v_add_u32_e32 v123, s1, v172
	global_load_dwordx4 v[116:119], v123, s[94:95]
	s_lshr_b32 s1, s0, 11
	s_mul_i32 s1, s1, 0x1800000
	s_and_b32 s2, s0, 0x7ff
	s_mul_i32 s2, s2, 0x600
	s_add_i32 s1, s1, s2
	v_add_u32_e32 v123, s1, v177
	global_load_dword v120, v123, s[94:95]
	s_lshl_b32 s1, s0, 11
	v_add_u32_e32 v123, s1, v174
	global_load_dword v121, v123, s[94:95]
	s_mul_i32 s1, s0, 0x1900
	v_add_u32_e32 v123, s1, v175
	global_load_ushort v122, v123, s[94:95]
	s_add_i32 s0, vcc_lo, 3
	s_lshl_b32 s1, s0, 7
	v_add_u32_e32 v131, s1, v172
	global_load_dwordx4 v[124:127], v131, s[94:95]
	s_lshr_b32 s1, s0, 11
	s_mul_i32 s1, s1, 0x1800000
	s_and_b32 s2, s0, 0x7ff
	s_mul_i32 s2, s2, 0x600
	s_add_i32 s1, s1, s2
	v_add_u32_e32 v131, s1, v177
	global_load_dword v128, v131, s[94:95]
	s_lshl_b32 s1, s0, 11
	v_add_u32_e32 v131, s1, v174
	global_load_dword v129, v131, s[94:95]
	s_mul_i32 s1, s0, 0x1900
	v_add_u32_e32 v131, s1, v175
	global_load_ushort v130, v131, s[94:95]
	s_waitcnt vmcnt(16)
	v_fmac_f32_e32 v139, v136, v138
	v_fmac_f32_e32 v147, v144, v146
	v_fmac_f32_e32 v155, v152, v154
	v_fmac_f32_e32 v163, v160, v162
	v_add_f32_dpp v178, v139, v139 quad_perm:[1,0,3,2] row_mask:0xf bank_mask:0xf bound_ctrl:1
	v_add_f32_dpp v179, v147, v147 quad_perm:[1,0,3,2] row_mask:0xf bank_mask:0xf bound_ctrl:1
	v_add_f32_dpp v180, v155, v155 quad_perm:[1,0,3,2] row_mask:0xf bank_mask:0xf bound_ctrl:1
	v_add_f32_dpp v181, v163, v163 quad_perm:[1,0,3,2] row_mask:0xf bank_mask:0xf bound_ctrl:1
	v_add_f32_dpp v178, v178, v178 quad_perm:[2,3,0,1] row_mask:0xf bank_mask:0xf bound_ctrl:1
	v_add_f32_dpp v179, v179, v179 quad_perm:[2,3,0,1] row_mask:0xf bank_mask:0xf bound_ctrl:1
	v_add_f32_dpp v180, v180, v180 quad_perm:[2,3,0,1] row_mask:0xf bank_mask:0xf bound_ctrl:1
	v_add_f32_dpp v181, v181, v181 quad_perm:[2,3,0,1] row_mask:0xf bank_mask:0xf bound_ctrl:1
	v_add_f32_dpp v178, v178, v178 row_half_mirror row_mask:0xf bank_mask:0xf bound_ctrl:1
	v_add_f32_dpp v179, v179, v179 row_half_mirror row_mask:0xf bank_mask:0xf bound_ctrl:1
	v_add_f32_dpp v180, v180, v180 row_half_mirror row_mask:0xf bank_mask:0xf bound_ctrl:1
	v_add_f32_dpp v181, v181, v181 row_half_mirror row_mask:0xf bank_mask:0xf bound_ctrl:1
	v_add_f32_dpp v178, v178, v178 row_mirror row_mask:0xf bank_mask:0xf bound_ctrl:1
	v_add_f32_dpp v179, v179, v179 row_mirror row_mask:0xf bank_mask:0xf bound_ctrl:1
	v_add_f32_dpp v180, v180, v180 row_mirror row_mask:0xf bank_mask:0xf bound_ctrl:1
	v_add_f32_dpp v181, v181, v181 row_mirror row_mask:0xf bank_mask:0xf bound_ctrl:1
	v_mov_b32_e32 v182, v65
	v_mov_b32_e32 v183, v65
	v_mov_b32_e32 v184, v65
	v_mov_b32_e32 v185, v65
	v_mov_b32_dpp v182, v178 row_bcast:15 row_mask:0xa bank_mask:0xf
	v_mov_b32_dpp v183, v179 row_bcast:15 row_mask:0xa bank_mask:0xf
	v_mov_b32_dpp v184, v180 row_bcast:15 row_mask:0xa bank_mask:0xf
	v_mov_b32_dpp v185, v181 row_bcast:15 row_mask:0xa bank_mask:0xf
	v_add_f32_e32 v178, v178, v182
	v_add_f32_e32 v179, v179, v183
	v_add_f32_e32 v180, v180, v184
	v_add_f32_e32 v181, v181, v185
	v_mov_b32_e32 v182, v65
	v_mov_b32_e32 v183, v65
	v_mov_b32_e32 v184, v65
	v_mov_b32_e32 v185, v65
	v_mov_b32_dpp v182, v178 row_bcast:31 row_mask:0xc bank_mask:0xf
	v_mov_b32_dpp v183, v179 row_bcast:31 row_mask:0xc bank_mask:0xf
	v_mov_b32_dpp v184, v180 row_bcast:31 row_mask:0xc bank_mask:0xf
	v_mov_b32_dpp v185, v181 row_bcast:31 row_mask:0xc bank_mask:0xf
	v_add_f32_e32 v178, v178, v182
	v_add_f32_e32 v179, v179, v183
	v_add_f32_e32 v180, v180, v184
	v_add_f32_e32 v181, v181, v185
	v_readlane_b32 s0, v178, 63
	v_readlane_b32 s1, v179, 63
	v_readlane_b32 s2, v180, 63
	v_readlane_b32 s20, v181, 63
	v_lshlrev_b32_e32 v140, 16, v140
	v_lshlrev_b32_e32 v148, 16, v148
	v_lshlrev_b32_e32 v156, 16, v156
	v_lshlrev_b32_e32 v164, 16, v164
	v_fmac_f32_e32 v139, s0, v193
	v_fmac_f32_e32 v147, s1, v193
	v_fmac_f32_e32 v155, s2, v193
	v_fmac_f32_e32 v163, s20, v193
	v_mul_f32_e32 v178, v139, v139
	v_mul_f32_e32 v179, v147, v147
	v_mul_f32_e32 v180, v155, v155
	v_mul_f32_e32 v181, v163, v163
	v_mov_b32_e32 v182, v65
	v_mov_b32_e32 v183, v65
	v_mov_b32_e32 v184, v65
	v_mov_b32_e32 v185, v65
	v_mov_b32_dpp v182, v178 quad_perm:[1,0,3,2] row_mask:0xf bank_mask:0xf
	v_mov_b32_dpp v183, v179 quad_perm:[1,0,3,2] row_mask:0xf bank_mask:0xf
	v_mov_b32_dpp v184, v180 quad_perm:[1,0,3,2] row_mask:0xf bank_mask:0xf
	v_mov_b32_dpp v185, v181 quad_perm:[1,0,3,2] row_mask:0xf bank_mask:0xf
	v_fmac_f32_e32 v182, v139, v139
	v_fmac_f32_e32 v183, v147, v147
	v_fmac_f32_e32 v184, v155, v155
	v_fmac_f32_e32 v185, v163, v163
	v_mov_b32_e32 v178, v182
	v_mov_b32_e32 v179, v183
	v_mov_b32_e32 v180, v184
	v_mov_b32_e32 v181, v185
	v_add_f32_dpp v178, v178, v178 quad_perm:[2,3,0,1] row_mask:0xf bank_mask:0xf bound_ctrl:1
	v_add_f32_dpp v179, v179, v179 quad_perm:[2,3,0,1] row_mask:0xf bank_mask:0xf bound_ctrl:1
	v_add_f32_dpp v180, v180, v180 quad_perm:[2,3,0,1] row_mask:0xf bank_mask:0xf bound_ctrl:1
	v_add_f32_dpp v181, v181, v181 quad_perm:[2,3,0,1] row_mask:0xf bank_mask:0xf bound_ctrl:1
	v_add_f32_dpp v178, v178, v178 row_half_mirror row_mask:0xf bank_mask:0xf bound_ctrl:1
	v_add_f32_dpp v179, v179, v179 row_half_mirror row_mask:0xf bank_mask:0xf bound_ctrl:1
	v_add_f32_dpp v180, v180, v180 row_half_mirror row_mask:0xf bank_mask:0xf bound_ctrl:1
	v_add_f32_dpp v181, v181, v181 row_half_mirror row_mask:0xf bank_mask:0xf bound_ctrl:1
	v_add_f32_dpp v178, v178, v178 row_mirror row_mask:0xf bank_mask:0xf bound_ctrl:1
	v_add_f32_dpp v179, v179, v179 row_mirror row_mask:0xf bank_mask:0xf bound_ctrl:1
	v_add_f32_dpp v180, v180, v180 row_mirror row_mask:0xf bank_mask:0xf bound_ctrl:1
	v_add_f32_dpp v181, v181, v181 row_mirror row_mask:0xf bank_mask:0xf bound_ctrl:1
	v_mov_b32_e32 v182, v65
	v_mov_b32_e32 v183, v65
	v_mov_b32_e32 v184, v65
	v_mov_b32_e32 v185, v65
	v_mov_b32_dpp v182, v178 row_bcast:15 row_mask:0xa bank_mask:0xf
	v_mov_b32_dpp v183, v179 row_bcast:15 row_mask:0xa bank_mask:0xf
	v_mov_b32_dpp v184, v180 row_bcast:15 row_mask:0xa bank_mask:0xf
	v_mov_b32_dpp v185, v181 row_bcast:15 row_mask:0xa bank_mask:0xf
	v_add_f32_e32 v178, v178, v182
	v_add_f32_e32 v179, v179, v183
	v_add_f32_e32 v180, v180, v184
	v_add_f32_e32 v181, v181, v185
	v_mov_b32_e32 v182, v65
	v_mov_b32_e32 v183, v65
	v_mov_b32_e32 v184, v65
	v_mov_b32_e32 v185, v65
	v_mov_b32_dpp v182, v178 row_bcast:31 row_mask:0xc bank_mask:0xf
	v_mov_b32_dpp v183, v179 row_bcast:31 row_mask:0xc bank_mask:0xf
	v_mov_b32_dpp v184, v180 row_bcast:31 row_mask:0xc bank_mask:0xf
	v_mov_b32_dpp v185, v181 row_bcast:31 row_mask:0xc bank_mask:0xf
	v_add_f32_e32 v178, v178, v182
	v_add_f32_e32 v179, v179, v183
	v_add_f32_e32 v180, v180, v184
	v_add_f32_e32 v181, v181, v185
	v_readlane_b32 s0, v178, 63
	v_readlane_b32 s1, v179, 63
	v_readlane_b32 s2, v180, 63
	v_readlane_b32 s20, v181, 63
	v_mul_f32_e32 v182, 0xbfb8aa3b, v140
	v_mul_f32_e32 v183, 0xbfb8aa3b, v148
	v_mul_f32_e32 v184, 0xbfb8aa3b, v156
	v_mul_f32_e32 v185, 0xbfb8aa3b, v164
	v_fma_f32 v178, s0, v194, v189
	v_fma_f32 v179, s1, v194, v189
	v_fma_f32 v180, s2, v194, v189
	v_fma_f32 v181, s20, v194, v189
	v_exp_f32_e32 v182, v182
	v_exp_f32_e32 v183, v183
	v_exp_f32_e32 v184, v184
	v_exp_f32_e32 v185, v185
	v_rsq_f32_e32 v178, v178
	v_rsq_f32_e32 v179, v179
	v_rsq_f32_e32 v180, v180
	v_rsq_f32_e32 v181, v181
	v_add_f32_e32 v182, 1.0, v182
	v_add_f32_e32 v183, 1.0, v183
	v_add_f32_e32 v184, 1.0, v184
	v_add_f32_e32 v185, 1.0, v185
	v_mul_f32_e32 v178, v139, v178
	v_mul_f32_e32 v179, v147, v179
	v_mul_f32_e32 v180, v155, v180
	v_mul_f32_e32 v181, v163, v181
	v_rcp_f32_e32 v182, v182
	v_rcp_f32_e32 v183, v183
	v_rcp_f32_e32 v184, v184
	v_rcp_f32_e32 v185, v185
	v_fma_f32 v178, v42, v178, v43
	v_fma_f32 v179, v42, v179, v43
	v_fma_f32 v180, v42, v180, v43
	v_fma_f32 v181, v42, v181, v43
	v_fmac_f32_e32 v178, v134, v138
	v_fmac_f32_e32 v179, v142, v146
	v_fmac_f32_e32 v180, v150, v154
	v_fmac_f32_e32 v181, v158, v162
	v_mul_f32_e32 v182, v182, v140
	v_mul_f32_e32 v183, v183, v148
	v_mul_f32_e32 v184, v184, v156
	v_mul_f32_e32 v185, v185, v164
	v_mul_f32_e32 v178, v182, v178
	v_mul_f32_e32 v179, v183, v179
	v_mul_f32_e32 v180, v184, v180
	v_mul_f32_e32 v181, v185, v181
	v_bfe_u32 v182, v178, 16, 1
	v_bfe_u32 v183, v179, 16, 1
	v_bfe_u32 v184, v180, 16, 1
	v_bfe_u32 v185, v181, 16, 1
	v_add3_u32 v178, v178, v182, s27
	v_add3_u32 v179, v179, v183, s27
	v_add3_u32 v180, v180, v184, s27
	v_add3_u32 v181, v181, v185, s27
	s_add_i32 s0, s24, 0
	s_lshl_b32 s0, s0, 11
	v_add_u32_e32 v182, s0, v176
	s_add_i32 s0, s24, 1
	s_lshl_b32 s0, s0, 11
	v_add_u32_e32 v183, s0, v176
	s_add_i32 s0, s24, 2
	s_lshl_b32 s0, s0, 11
	v_add_u32_e32 v184, s0, v176
	s_add_i32 s0, s24, 3
	s_lshl_b32 s0, s0, 11
	v_add_u32_e32 v185, s0, v176
	global_store_short_d16_hi v182, v178, s[94:95]
	global_store_short_d16_hi v183, v179, s[94:95]
	global_store_short_d16_hi v184, v180, s[94:95]
	global_store_short_d16_hi v185, v181, s[94:95]
	s_mov_b32 s24, vcc_lo
	s_branch .Lb3_loop
.Lb3_last0:
	s_waitcnt vmcnt(0)
	v_fmac_f32_e32 v105, v102, v104
	v_fmac_f32_e32 v113, v110, v112
	v_fmac_f32_e32 v121, v118, v120
	v_fmac_f32_e32 v129, v126, v128
	v_add_f32_dpp v178, v105, v105 quad_perm:[1,0,3,2] row_mask:0xf bank_mask:0xf bound_ctrl:1
	v_add_f32_dpp v179, v113, v113 quad_perm:[1,0,3,2] row_mask:0xf bank_mask:0xf bound_ctrl:1
	v_add_f32_dpp v180, v121, v121 quad_perm:[1,0,3,2] row_mask:0xf bank_mask:0xf bound_ctrl:1
	v_add_f32_dpp v181, v129, v129 quad_perm:[1,0,3,2] row_mask:0xf bank_mask:0xf bound_ctrl:1
	v_add_f32_dpp v178, v178, v178 quad_perm:[2,3,0,1] row_mask:0xf bank_mask:0xf bound_ctrl:1
	v_add_f32_dpp v179, v179, v179 quad_perm:[2,3,0,1] row_mask:0xf bank_mask:0xf bound_ctrl:1
	v_add_f32_dpp v180, v180, v180 quad_perm:[2,3,0,1] row_mask:0xf bank_mask:0xf bound_ctrl:1
	v_add_f32_dpp v181, v181, v181 quad_perm:[2,3,0,1] row_mask:0xf bank_mask:0xf bound_ctrl:1
	v_add_f32_dpp v178, v178, v178 row_half_mirror row_mask:0xf bank_mask:0xf bound_ctrl:1
	v_add_f32_dpp v179, v179, v179 row_half_mirror row_mask:0xf bank_mask:0xf bound_ctrl:1
	v_add_f32_dpp v180, v180, v180 row_half_mirror row_mask:0xf bank_mask:0xf bound_ctrl:1
	v_add_f32_dpp v181, v181, v181 row_half_mirror row_mask:0xf bank_mask:0xf bound_ctrl:1
	v_add_f32_dpp v178, v178, v178 row_mirror row_mask:0xf bank_mask:0xf bound_ctrl:1
	v_add_f32_dpp v179, v179, v179 row_mirror row_mask:0xf bank_mask:0xf bound_ctrl:1
	v_add_f32_dpp v180, v180, v180 row_mirror row_mask:0xf bank_mask:0xf bound_ctrl:1
	v_add_f32_dpp v181, v181, v181 row_mirror row_mask:0xf bank_mask:0xf bound_ctrl:1
	v_mov_b32_e32 v182, v65
	v_mov_b32_e32 v183, v65
	v_mov_b32_e32 v184, v65
	v_mov_b32_e32 v185, v65
	v_mov_b32_dpp v182, v178 row_bcast:15 row_mask:0xa bank_mask:0xf
	v_mov_b32_dpp v183, v179 row_bcast:15 row_mask:0xa bank_mask:0xf
	v_mov_b32_dpp v184, v180 row_bcast:15 row_mask:0xa bank_mask:0xf
	v_mov_b32_dpp v185, v181 row_bcast:15 row_mask:0xa bank_mask:0xf
	v_add_f32_e32 v178, v178, v182
	v_add_f32_e32 v179, v179, v183
	v_add_f32_e32 v180, v180, v184
	v_add_f32_e32 v181, v181, v185
	v_mov_b32_e32 v182, v65
	v_mov_b32_e32 v183, v65
	v_mov_b32_e32 v184, v65
	v_mov_b32_e32 v185, v65
	v_mov_b32_dpp v182, v178 row_bcast:31 row_mask:0xc bank_mask:0xf
	v_mov_b32_dpp v183, v179 row_bcast:31 row_mask:0xc bank_mask:0xf
	v_mov_b32_dpp v184, v180 row_bcast:31 row_mask:0xc bank_mask:0xf
	v_mov_b32_dpp v185, v181 row_bcast:31 row_mask:0xc bank_mask:0xf
	v_add_f32_e32 v178, v178, v182
	v_add_f32_e32 v179, v179, v183
	v_add_f32_e32 v180, v180, v184
	v_add_f32_e32 v181, v181, v185
	v_readlane_b32 s0, v178, 63
	v_readlane_b32 s1, v179, 63
	v_readlane_b32 s2, v180, 63
	v_readlane_b32 s20, v181, 63
	v_lshlrev_b32_e32 v106, 16, v106
	v_lshlrev_b32_e32 v114, 16, v114
	v_lshlrev_b32_e32 v122, 16, v122
	v_lshlrev_b32_e32 v130, 16, v130
	v_fmac_f32_e32 v105, s0, v193
	v_fmac_f32_e32 v113, s1, v193
	v_fmac_f32_e32 v121, s2, v193
	v_fmac_f32_e32 v129, s20, v193
	v_mul_f32_e32 v178, v105, v105
	v_mul_f32_e32 v179, v113, v113
	v_mul_f32_e32 v180, v121, v121
	v_mul_f32_e32 v181, v129, v129
	v_mov_b32_e32 v182, v65
	v_mov_b32_e32 v183, v65
	v_mov_b32_e32 v184, v65
	v_mov_b32_e32 v185, v65
	v_mov_b32_dpp v182, v178 quad_perm:[1,0,3,2] row_mask:0xf bank_mask:0xf
	v_mov_b32_dpp v183, v179 quad_perm:[1,0,3,2] row_mask:0xf bank_mask:0xf
	v_mov_b32_dpp v184, v180 quad_perm:[1,0,3,2] row_mask:0xf bank_mask:0xf
	v_mov_b32_dpp v185, v181 quad_perm:[1,0,3,2] row_mask:0xf bank_mask:0xf
	v_fmac_f32_e32 v182, v105, v105
	v_fmac_f32_e32 v183, v113, v113
	v_fmac_f32_e32 v184, v121, v121
	v_fmac_f32_e32 v185, v129, v129
	v_mov_b32_e32 v178, v182
	v_mov_b32_e32 v179, v183
	v_mov_b32_e32 v180, v184
	v_mov_b32_e32 v181, v185
	v_add_f32_dpp v178, v178, v178 quad_perm:[2,3,0,1] row_mask:0xf bank_mask:0xf bound_ctrl:1
	v_add_f32_dpp v179, v179, v179 quad_perm:[2,3,0,1] row_mask:0xf bank_mask:0xf bound_ctrl:1
	v_add_f32_dpp v180, v180, v180 quad_perm:[2,3,0,1] row_mask:0xf bank_mask:0xf bound_ctrl:1
	v_add_f32_dpp v181, v181, v181 quad_perm:[2,3,0,1] row_mask:0xf bank_mask:0xf bound_ctrl:1
	v_add_f32_dpp v178, v178, v178 row_half_mirror row_mask:0xf bank_mask:0xf bound_ctrl:1
	v_add_f32_dpp v179, v179, v179 row_half_mirror row_mask:0xf bank_mask:0xf bound_ctrl:1
	v_add_f32_dpp v180, v180, v180 row_half_mirror row_mask:0xf bank_mask:0xf bound_ctrl:1
	v_add_f32_dpp v181, v181, v181 row_half_mirror row_mask:0xf bank_mask:0xf bound_ctrl:1
	v_add_f32_dpp v178, v178, v178 row_mirror row_mask:0xf bank_mask:0xf bound_ctrl:1
	v_add_f32_dpp v179, v179, v179 row_mirror row_mask:0xf bank_mask:0xf bound_ctrl:1
	v_add_f32_dpp v180, v180, v180 row_mirror row_mask:0xf bank_mask:0xf bound_ctrl:1
	v_add_f32_dpp v181, v181, v181 row_mirror row_mask:0xf bank_mask:0xf bound_ctrl:1
	v_mov_b32_e32 v182, v65
	v_mov_b32_e32 v183, v65
	v_mov_b32_e32 v184, v65
	v_mov_b32_e32 v185, v65
	v_mov_b32_dpp v182, v178 row_bcast:15 row_mask:0xa bank_mask:0xf
	v_mov_b32_dpp v183, v179 row_bcast:15 row_mask:0xa bank_mask:0xf
	v_mov_b32_dpp v184, v180 row_bcast:15 row_mask:0xa bank_mask:0xf
	v_mov_b32_dpp v185, v181 row_bcast:15 row_mask:0xa bank_mask:0xf
	v_add_f32_e32 v178, v178, v182
	v_add_f32_e32 v179, v179, v183
	v_add_f32_e32 v180, v180, v184
	v_add_f32_e32 v181, v181, v185
	v_mov_b32_e32 v182, v65
	v_mov_b32_e32 v183, v65
	v_mov_b32_e32 v184, v65
	v_mov_b32_e32 v185, v65
	v_mov_b32_dpp v182, v178 row_bcast:31 row_mask:0xc bank_mask:0xf
	v_mov_b32_dpp v183, v179 row_bcast:31 row_mask:0xc bank_mask:0xf
	v_mov_b32_dpp v184, v180 row_bcast:31 row_mask:0xc bank_mask:0xf
	v_mov_b32_dpp v185, v181 row_bcast:31 row_mask:0xc bank_mask:0xf
	v_add_f32_e32 v178, v178, v182
	v_add_f32_e32 v179, v179, v183
	v_add_f32_e32 v180, v180, v184
	v_add_f32_e32 v181, v181, v185
	v_readlane_b32 s0, v178, 63
	v_readlane_b32 s1, v179, 63
	v_readlane_b32 s2, v180, 63
	v_readlane_b32 s20, v181, 63
	v_mul_f32_e32 v182, 0xbfb8aa3b, v106
	v_mul_f32_e32 v183, 0xbfb8aa3b, v114
	v_mul_f32_e32 v184, 0xbfb8aa3b, v122
	v_mul_f32_e32 v185, 0xbfb8aa3b, v130
	v_fma_f32 v178, s0, v194, v189
	v_fma_f32 v179, s1, v194, v189
	v_fma_f32 v180, s2, v194, v189
	v_fma_f32 v181, s20, v194, v189
	v_exp_f32_e32 v182, v182
	v_exp_f32_e32 v183, v183
	v_exp_f32_e32 v184, v184
	v_exp_f32_e32 v185, v185
	v_rsq_f32_e32 v178, v178
	v_rsq_f32_e32 v179, v179
	v_rsq_f32_e32 v180, v180
	v_rsq_f32_e32 v181, v181
	v_add_f32_e32 v182, 1.0, v182
	v_add_f32_e32 v183, 1.0, v183
	v_add_f32_e32 v184, 1.0, v184
	v_add_f32_e32 v185, 1.0, v185
	v_mul_f32_e32 v178, v105, v178
	v_mul_f32_e32 v179, v113, v179
	v_mul_f32_e32 v180, v121, v180
	v_mul_f32_e32 v181, v129, v181
	v_rcp_f32_e32 v182, v182
	v_rcp_f32_e32 v183, v183
	v_rcp_f32_e32 v184, v184
	v_rcp_f32_e32 v185, v185
	v_fma_f32 v178, v42, v178, v43
	v_fma_f32 v179, v42, v179, v43
	v_fma_f32 v180, v42, v180, v43
	v_fma_f32 v181, v42, v181, v43
	v_fmac_f32_e32 v178, v100, v104
	v_fmac_f32_e32 v179, v108, v112
	v_fmac_f32_e32 v180, v116, v120
	v_fmac_f32_e32 v181, v124, v128
	v_mul_f32_e32 v182, v182, v106
	v_mul_f32_e32 v183, v183, v114
	v_mul_f32_e32 v184, v184, v122
	v_mul_f32_e32 v185, v185, v130
	v_mul_f32_e32 v178, v182, v178
	v_mul_f32_e32 v179, v183, v179
	v_mul_f32_e32 v180, v184, v180
	v_mul_f32_e32 v181, v185, v181
	v_bfe_u32 v182, v178, 16, 1
	v_bfe_u32 v183, v179, 16, 1
	v_bfe_u32 v184, v180, 16, 1
	v_bfe_u32 v185, v181, 16, 1
	v_add3_u32 v178, v178, v182, s27
	v_add3_u32 v179, v179, v183, s27
	v_add3_u32 v180, v180, v184, s27
	v_add3_u32 v181, v181, v185, s27
	s_add_i32 s0, s24, 0
	s_lshl_b32 s0, s0, 11
	v_add_u32_e32 v182, s0, v176
	s_add_i32 s0, s24, 1
	s_lshl_b32 s0, s0, 11
	v_add_u32_e32 v183, s0, v176
	s_add_i32 s0, s24, 2
	s_lshl_b32 s0, s0, 11
	v_add_u32_e32 v184, s0, v176
	s_add_i32 s0, s24, 3
	s_lshl_b32 s0, s0, 11
	v_add_u32_e32 v185, s0, v176
	global_store_short_d16_hi v182, v178, s[94:95]
	global_store_short_d16_hi v183, v179, s[94:95]
	global_store_short_d16_hi v184, v180, s[94:95]
	global_store_short_d16_hi v185, v181, s[94:95]
	s_branch .LBB0_197
.Lb3_last1:
	s_waitcnt vmcnt(0)
	v_fmac_f32_e32 v139, v136, v138
	v_fmac_f32_e32 v147, v144, v146
	v_fmac_f32_e32 v155, v152, v154
	v_fmac_f32_e32 v163, v160, v162
	v_add_f32_dpp v178, v139, v139 quad_perm:[1,0,3,2] row_mask:0xf bank_mask:0xf bound_ctrl:1
	v_add_f32_dpp v179, v147, v147 quad_perm:[1,0,3,2] row_mask:0xf bank_mask:0xf bound_ctrl:1
	v_add_f32_dpp v180, v155, v155 quad_perm:[1,0,3,2] row_mask:0xf bank_mask:0xf bound_ctrl:1
	v_add_f32_dpp v181, v163, v163 quad_perm:[1,0,3,2] row_mask:0xf bank_mask:0xf bound_ctrl:1
	v_add_f32_dpp v178, v178, v178 quad_perm:[2,3,0,1] row_mask:0xf bank_mask:0xf bound_ctrl:1
	v_add_f32_dpp v179, v179, v179 quad_perm:[2,3,0,1] row_mask:0xf bank_mask:0xf bound_ctrl:1
	v_add_f32_dpp v180, v180, v180 quad_perm:[2,3,0,1] row_mask:0xf bank_mask:0xf bound_ctrl:1
	v_add_f32_dpp v181, v181, v181 quad_perm:[2,3,0,1] row_mask:0xf bank_mask:0xf bound_ctrl:1
	v_add_f32_dpp v178, v178, v178 row_half_mirror row_mask:0xf bank_mask:0xf bound_ctrl:1
	v_add_f32_dpp v179, v179, v179 row_half_mirror row_mask:0xf bank_mask:0xf bound_ctrl:1
	v_add_f32_dpp v180, v180, v180 row_half_mirror row_mask:0xf bank_mask:0xf bound_ctrl:1
	v_add_f32_dpp v181, v181, v181 row_half_mirror row_mask:0xf bank_mask:0xf bound_ctrl:1
	v_add_f32_dpp v178, v178, v178 row_mirror row_mask:0xf bank_mask:0xf bound_ctrl:1
	v_add_f32_dpp v179, v179, v179 row_mirror row_mask:0xf bank_mask:0xf bound_ctrl:1
	v_add_f32_dpp v180, v180, v180 row_mirror row_mask:0xf bank_mask:0xf bound_ctrl:1
	v_add_f32_dpp v181, v181, v181 row_mirror row_mask:0xf bank_mask:0xf bound_ctrl:1
	v_mov_b32_e32 v182, v65
	v_mov_b32_e32 v183, v65
	v_mov_b32_e32 v184, v65
	v_mov_b32_e32 v185, v65
	v_mov_b32_dpp v182, v178 row_bcast:15 row_mask:0xa bank_mask:0xf
	v_mov_b32_dpp v183, v179 row_bcast:15 row_mask:0xa bank_mask:0xf
	v_mov_b32_dpp v184, v180 row_bcast:15 row_mask:0xa bank_mask:0xf
	v_mov_b32_dpp v185, v181 row_bcast:15 row_mask:0xa bank_mask:0xf
	v_add_f32_e32 v178, v178, v182
	v_add_f32_e32 v179, v179, v183
	v_add_f32_e32 v180, v180, v184
	v_add_f32_e32 v181, v181, v185
	v_mov_b32_e32 v182, v65
	v_mov_b32_e32 v183, v65
	v_mov_b32_e32 v184, v65
	v_mov_b32_e32 v185, v65
	v_mov_b32_dpp v182, v178 row_bcast:31 row_mask:0xc bank_mask:0xf
	v_mov_b32_dpp v183, v179 row_bcast:31 row_mask:0xc bank_mask:0xf
	v_mov_b32_dpp v184, v180 row_bcast:31 row_mask:0xc bank_mask:0xf
	v_mov_b32_dpp v185, v181 row_bcast:31 row_mask:0xc bank_mask:0xf
	v_add_f32_e32 v178, v178, v182
	v_add_f32_e32 v179, v179, v183
	v_add_f32_e32 v180, v180, v184
	v_add_f32_e32 v181, v181, v185
	v_readlane_b32 s0, v178, 63
	v_readlane_b32 s1, v179, 63
	v_readlane_b32 s2, v180, 63
	v_readlane_b32 s20, v181, 63
	v_lshlrev_b32_e32 v140, 16, v140
	v_lshlrev_b32_e32 v148, 16, v148
	v_lshlrev_b32_e32 v156, 16, v156
	v_lshlrev_b32_e32 v164, 16, v164
	v_fmac_f32_e32 v139, s0, v193
	v_fmac_f32_e32 v147, s1, v193
	v_fmac_f32_e32 v155, s2, v193
	v_fmac_f32_e32 v163, s20, v193
	v_mul_f32_e32 v178, v139, v139
	v_mul_f32_e32 v179, v147, v147
	v_mul_f32_e32 v180, v155, v155
	v_mul_f32_e32 v181, v163, v163
	v_mov_b32_e32 v182, v65
	v_mov_b32_e32 v183, v65
	v_mov_b32_e32 v184, v65
	v_mov_b32_e32 v185, v65
	v_mov_b32_dpp v182, v178 quad_perm:[1,0,3,2] row_mask:0xf bank_mask:0xf
	v_mov_b32_dpp v183, v179 quad_perm:[1,0,3,2] row_mask:0xf bank_mask:0xf
	v_mov_b32_dpp v184, v180 quad_perm:[1,0,3,2] row_mask:0xf bank_mask:0xf
	v_mov_b32_dpp v185, v181 quad_perm:[1,0,3,2] row_mask:0xf bank_mask:0xf
	v_fmac_f32_e32 v182, v139, v139
	v_fmac_f32_e32 v183, v147, v147
	v_fmac_f32_e32 v184, v155, v155
	v_fmac_f32_e32 v185, v163, v163
	v_mov_b32_e32 v178, v182
	v_mov_b32_e32 v179, v183
	v_mov_b32_e32 v180, v184
	v_mov_b32_e32 v181, v185
	v_add_f32_dpp v178, v178, v178 quad_perm:[2,3,0,1] row_mask:0xf bank_mask:0xf bound_ctrl:1
	v_add_f32_dpp v179, v179, v179 quad_perm:[2,3,0,1] row_mask:0xf bank_mask:0xf bound_ctrl:1
	v_add_f32_dpp v180, v180, v180 quad_perm:[2,3,0,1] row_mask:0xf bank_mask:0xf bound_ctrl:1
	v_add_f32_dpp v181, v181, v181 quad_perm:[2,3,0,1] row_mask:0xf bank_mask:0xf bound_ctrl:1
	v_add_f32_dpp v178, v178, v178 row_half_mirror row_mask:0xf bank_mask:0xf bound_ctrl:1
	v_add_f32_dpp v179, v179, v179 row_half_mirror row_mask:0xf bank_mask:0xf bound_ctrl:1
	v_add_f32_dpp v180, v180, v180 row_half_mirror row_mask:0xf bank_mask:0xf bound_ctrl:1
	v_add_f32_dpp v181, v181, v181 row_half_mirror row_mask:0xf bank_mask:0xf bound_ctrl:1
	v_add_f32_dpp v178, v178, v178 row_mirror row_mask:0xf bank_mask:0xf bound_ctrl:1
	v_add_f32_dpp v179, v179, v179 row_mirror row_mask:0xf bank_mask:0xf bound_ctrl:1
	v_add_f32_dpp v180, v180, v180 row_mirror row_mask:0xf bank_mask:0xf bound_ctrl:1
	v_add_f32_dpp v181, v181, v181 row_mirror row_mask:0xf bank_mask:0xf bound_ctrl:1
	v_mov_b32_e32 v182, v65
	v_mov_b32_e32 v183, v65
	v_mov_b32_e32 v184, v65
	v_mov_b32_e32 v185, v65
	v_mov_b32_dpp v182, v178 row_bcast:15 row_mask:0xa bank_mask:0xf
	v_mov_b32_dpp v183, v179 row_bcast:15 row_mask:0xa bank_mask:0xf
	v_mov_b32_dpp v184, v180 row_bcast:15 row_mask:0xa bank_mask:0xf
	v_mov_b32_dpp v185, v181 row_bcast:15 row_mask:0xa bank_mask:0xf
	v_add_f32_e32 v178, v178, v182
	v_add_f32_e32 v179, v179, v183
	v_add_f32_e32 v180, v180, v184
	v_add_f32_e32 v181, v181, v185
	v_mov_b32_e32 v182, v65
	v_mov_b32_e32 v183, v65
	v_mov_b32_e32 v184, v65
	v_mov_b32_e32 v185, v65
	v_mov_b32_dpp v182, v178 row_bcast:31 row_mask:0xc bank_mask:0xf
	v_mov_b32_dpp v183, v179 row_bcast:31 row_mask:0xc bank_mask:0xf
	v_mov_b32_dpp v184, v180 row_bcast:31 row_mask:0xc bank_mask:0xf
	v_mov_b32_dpp v185, v181 row_bcast:31 row_mask:0xc bank_mask:0xf
	v_add_f32_e32 v178, v178, v182
	v_add_f32_e32 v179, v179, v183
	v_add_f32_e32 v180, v180, v184
	v_add_f32_e32 v181, v181, v185
	v_readlane_b32 s0, v178, 63
	v_readlane_b32 s1, v179, 63
	v_readlane_b32 s2, v180, 63
	v_readlane_b32 s20, v181, 63
	v_mul_f32_e32 v182, 0xbfb8aa3b, v140
	v_mul_f32_e32 v183, 0xbfb8aa3b, v148
	v_mul_f32_e32 v184, 0xbfb8aa3b, v156
	v_mul_f32_e32 v185, 0xbfb8aa3b, v164
	v_fma_f32 v178, s0, v194, v189
	v_fma_f32 v179, s1, v194, v189
	v_fma_f32 v180, s2, v194, v189
	v_fma_f32 v181, s20, v194, v189
	v_exp_f32_e32 v182, v182
	v_exp_f32_e32 v183, v183
	v_exp_f32_e32 v184, v184
	v_exp_f32_e32 v185, v185
	v_rsq_f32_e32 v178, v178
	v_rsq_f32_e32 v179, v179
	v_rsq_f32_e32 v180, v180
	v_rsq_f32_e32 v181, v181
	v_add_f32_e32 v182, 1.0, v182
	v_add_f32_e32 v183, 1.0, v183
	v_add_f32_e32 v184, 1.0, v184
	v_add_f32_e32 v185, 1.0, v185
	v_mul_f32_e32 v178, v139, v178
	v_mul_f32_e32 v179, v147, v179
	v_mul_f32_e32 v180, v155, v180
	v_mul_f32_e32 v181, v163, v181
	v_rcp_f32_e32 v182, v182
	v_rcp_f32_e32 v183, v183
	v_rcp_f32_e32 v184, v184
	v_rcp_f32_e32 v185, v185
	v_fma_f32 v178, v42, v178, v43
	v_fma_f32 v179, v42, v179, v43
	v_fma_f32 v180, v42, v180, v43
	v_fma_f32 v181, v42, v181, v43
	v_fmac_f32_e32 v178, v134, v138
	v_fmac_f32_e32 v179, v142, v146
	v_fmac_f32_e32 v180, v150, v154
	v_fmac_f32_e32 v181, v158, v162
	v_mul_f32_e32 v182, v182, v140
	v_mul_f32_e32 v183, v183, v148
	v_mul_f32_e32 v184, v184, v156
	v_mul_f32_e32 v185, v185, v164
	v_mul_f32_e32 v178, v182, v178
	v_mul_f32_e32 v179, v183, v179
	v_mul_f32_e32 v180, v184, v180
	v_mul_f32_e32 v181, v185, v181
	v_bfe_u32 v182, v178, 16, 1
	v_bfe_u32 v183, v179, 16, 1
	v_bfe_u32 v184, v180, 16, 1
	v_bfe_u32 v185, v181, 16, 1
	v_add3_u32 v178, v178, v182, s27
	v_add3_u32 v179, v179, v183, s27
	v_add3_u32 v180, v180, v184, s27
	v_add3_u32 v181, v181, v185, s27
	s_add_i32 s0, s24, 0
	s_lshl_b32 s0, s0, 11
	v_add_u32_e32 v182, s0, v176
	s_add_i32 s0, s24, 1
	s_lshl_b32 s0, s0, 11
	v_add_u32_e32 v183, s0, v176
	s_add_i32 s0, s24, 2
	s_lshl_b32 s0, s0, 11
	v_add_u32_e32 v184, s0, v176
	s_add_i32 s0, s24, 3
	s_lshl_b32 s0, s0, 11
	v_add_u32_e32 v185, s0, v176
	global_store_short_d16_hi v182, v178, s[94:95]
	global_store_short_d16_hi v183, v179, s[94:95]
	global_store_short_d16_hi v184, v180, s[94:95]
	global_store_short_d16_hi v185, v181, s[94:95]
	s_branch .LBB0_197
